# GEMM P1/P4 epilogues: split v_pk_mul_f32 into scalar v_mul_f32 pairs (bit-identical)
# baseline (speedup 1.0000x reference)
; __device__ __forceinline__ unsigned cvt_pk_bf16(float lo, float hi) { unsigned r; asm volatile("v_cvt_pk_bf16_f32 %0, %1, %2" : "=v"(r) : "v"(lo), "v"(hi)); return r; }
;     __device__ __forceinline__ void operator()(const f32x4 (&acc)[2][2][4][2], const Unit& u, int wr, int wc, int fr, int fq, const float (&rsv)[8]) const {
;     ...
;         for (int ai = 0; ai < 2; ++ai)
; #pragma unroll
;             for (int m = 0; m < 4; ++m) { bf16_t* rowp = O + (size_t)(row0 + ai * HALF + m * 16) * ldc + col0; const float sc = RSC ? rsv[4 * ai + m] : 1.f;
; #pragma unroll
;                 for (int bj = 0; bj < 2; ++bj) { const f32x4 v0 = acc[ai][bj][m][0] * sc, v1 = acc[ai][bj][m][1] * sc;
;                     u32x4 w; w.x = cvt_pk_bf16(v0[0], v0[1]); w.y = cvt_pk_bf16(v0[2], v0[3]); w.z = cvt_pk_bf16(v1[0], v1[1]); w.w = cvt_pk_bf16(v1[2], v1[3]);
;                     *(u32x4*)(rowp + bj * HALF) = w; } }
.LBB0_126:
	s_lshl_b32 s15, s6, 8
	v_or_b32_e32 v158, s15, v149
	v_ashrrev_i32_e32 v159, 31, v158
	v_mad_i64_i32 v[160:161], s[2:3], v156, s0, 0
	v_lshl_add_u64 v[160:161], v[160:161], 1, s[78:79]
	v_lshlrev_b64 v[158:159], 1, v[158:159]
	v_lshl_add_u64 v[160:161], v[160:161], 0, v[158:159]
	s_waitcnt vmcnt(0)
	v_mul_f32_e32 v128, v128, v146
	v_mul_f32_e32 v129, v129, v146
	v_mul_f32_e32 v126, v126, v146
	v_mul_f32_e32 v127, v127, v146
	v_mul_f32_e32 v162, v124, v146
	v_mul_f32_e32 v163, v125, v146
	v_mul_f32_e32 v124, v122, v146
	v_mul_f32_e32 v125, v123, v146
	v_cvt_pk_bf16_f32 v122, v126, v127
	v_cvt_pk_bf16_f32 v123, v128, v129
	v_mul_f32_e32 v118, v118, v146
	v_mul_f32_e32 v119, v119, v146
	v_cvt_pk_bf16_f32 v124, v124, v125
	v_cvt_pk_bf16_f32 v125, v162, v163
	global_store_dwordx4 v[160:161], v[122:125], off
	v_mul_f32_e32 v120, v120, v146
	v_mul_f32_e32 v121, v121, v146
	v_mul_f32_e32 v114, v114, v150
	v_mul_f32_e32 v115, v115, v150
	v_mul_f32_e32 v122, v112, v146
	v_mul_f32_e32 v123, v113, v146
	v_mul_f32_e32 v112, v110, v146
	v_mul_f32_e32 v113, v111, v146
	v_cvt_pk_bf16_f32 v110, v118, v119
	v_cvt_pk_bf16_f32 v111, v120, v121
	v_mul_f32_e32 v102, v102, v150
	v_mul_f32_e32 v103, v103, v150
	v_cvt_pk_bf16_f32 v112, v112, v113
	v_cvt_pk_bf16_f32 v113, v122, v123
	global_store_dwordx4 v[160:161], v[110:113], off offset:256
	v_mul_f32_e32 v104, v104, v150
	v_mul_f32_e32 v105, v105, v150
	v_mul_f32_e32 v98, v98, v148
	v_mul_f32_e32 v99, v99, v148
	v_or_b32_e32 v110, 16, v156
	v_mad_i64_i32 v[110:111], s[2:3], v110, s0, 0
	v_lshl_add_u64 v[110:111], v[110:111], 1, s[78:79]
	v_lshl_add_u64 v[110:111], v[110:111], 0, v[158:159]
	v_mul_f32_e32 v112, v116, v150
	v_mul_f32_e32 v113, v117, v150
	v_mul_f32_e32 v116, v108, v150
	v_mul_f32_e32 v117, v109, v150
	v_mul_f32_e32 v108, v106, v150
	v_mul_f32_e32 v109, v107, v150
	v_cvt_pk_bf16_f32 v106, v114, v115
	v_cvt_pk_bf16_f32 v107, v112, v113
	v_mul_f32_e32 v86, v86, v148
	v_mul_f32_e32 v87, v87, v148
	v_cvt_pk_bf16_f32 v108, v108, v109
	v_cvt_pk_bf16_f32 v109, v116, v117
	global_store_dwordx4 v[110:111], v[106:109], off
	v_mul_f32_e32 v88, v88, v148
	v_mul_f32_e32 v89, v89, v148
	v_mul_f32_e32 v82, v82, v152
	v_mul_f32_e32 v83, v83, v152
	v_mul_f32_e32 v106, v96, v150
	v_mul_f32_e32 v107, v97, v150
	v_mul_f32_e32 v96, v94, v150
	v_mul_f32_e32 v97, v95, v150
	v_cvt_pk_bf16_f32 v94, v102, v103
	v_cvt_pk_bf16_f32 v95, v104, v105
	v_mul_f32_e32 v70, v70, v152
	v_mul_f32_e32 v71, v71, v152
	v_cvt_pk_bf16_f32 v96, v96, v97
	v_cvt_pk_bf16_f32 v97, v106, v107
	global_store_dwordx4 v[110:111], v[94:97], off offset:256
	v_mul_f32_e32 v72, v72, v152
	v_mul_f32_e32 v73, v73, v152
	v_mul_f32_e32 v64, v64, v144
	v_mul_f32_e32 v65, v65, v144
	v_or_b32_e32 v94, 32, v156
	v_mad_i64_i32 v[94:95], s[2:3], v94, s0, 0
	v_lshl_add_u64 v[94:95], v[94:95], 1, s[78:79]
	v_lshl_add_u64 v[94:95], v[94:95], 0, v[158:159]
	v_mul_f32_e32 v96, v100, v148
	v_mul_f32_e32 v97, v101, v148
	v_mul_f32_e32 v100, v92, v148
	v_mul_f32_e32 v101, v93, v148
	v_mul_f32_e32 v92, v90, v148
	v_mul_f32_e32 v93, v91, v148
	v_cvt_pk_bf16_f32 v90, v98, v99
	v_cvt_pk_bf16_f32 v91, v96, v97
	v_mul_f32_e32 v62, v62, v144
	v_mul_f32_e32 v63, v63, v144
	v_cvt_pk_bf16_f32 v92, v92, v93
	v_cvt_pk_bf16_f32 v93, v100, v101
	global_store_dwordx4 v[94:95], v[90:93], off
	v_mul_f32_e32 v54, v54, v144
	v_mul_f32_e32 v55, v55, v144
	v_mul_f32_e32 v56, v56, v144
	v_mul_f32_e32 v57, v57, v144
	v_mul_f32_e32 v90, v80, v148
	v_mul_f32_e32 v91, v81, v148
	v_mul_f32_e32 v80, v78, v148
	v_mul_f32_e32 v81, v79, v148
	v_cvt_pk_bf16_f32 v78, v86, v87
	v_cvt_pk_bf16_f32 v79, v88, v89
	v_mul_f32_e32 v50, v50, v145
	v_mul_f32_e32 v51, v51, v145
	v_cvt_pk_bf16_f32 v80, v80, v81
	v_cvt_pk_bf16_f32 v81, v90, v91
	global_store_dwordx4 v[94:95], v[78:81], off offset:256
	v_mul_f32_e32 v38, v38, v145
	v_mul_f32_e32 v39, v39, v145
	v_mul_f32_e32 v40, v40, v145
	v_mul_f32_e32 v41, v41, v145
	v_or_b32_e32 v78, 48, v156
	v_mad_i64_i32 v[78:79], s[2:3], v78, s0, 0
	v_lshl_add_u64 v[78:79], v[78:79], 1, s[78:79]
	v_lshl_add_u64 v[78:79], v[78:79], 0, v[158:159]
	v_mul_f32_e32 v80, v84, v152
	v_mul_f32_e32 v81, v85, v152
	v_mul_f32_e32 v84, v76, v152
	v_mul_f32_e32 v85, v77, v152
	v_mul_f32_e32 v76, v74, v152
	v_mul_f32_e32 v77, v75, v152
	v_cvt_pk_bf16_f32 v74, v82, v83
	v_cvt_pk_bf16_f32 v75, v80, v81
	v_mul_f32_e32 v34, v34, v154
; __device__ __forceinline__ unsigned cvt_pk_bf16(float lo, float hi) { unsigned r; asm volatile("v_cvt_pk_bf16_f32 %0, %1, %2" : "=v"(r) : "v"(lo), "v"(hi)); return r; }
;     __device__ __forceinline__ void operator()(const f32x4 (&acc)[2][2][4][2], const Unit& u, int wr, int wc, int fr, int fq, const float (&rsv)[8]) const {
;     ...
;         for (int ai = 0; ai < 2; ++ai)
; #pragma unroll
;             for (int m = 0; m < 4; ++m) { bf16_t* rowp = O + (size_t)(row0 + ai * HALF + m * 16) * ldc + col0; const float sc = RSC ? rsv[4 * ai + m] : 1.f;
; #pragma unroll
;                 for (int bj = 0; bj < 2; ++bj) { const f32x4 v0 = acc[ai][bj][m][0] * sc, v1 = acc[ai][bj][m][1] * sc;
;                     u32x4 w; w.x = cvt_pk_bf16(v0[0], v0[1]); w.y = cvt_pk_bf16(v0[2], v0[3]); w.z = cvt_pk_bf16(v1[0], v1[1]); w.w = cvt_pk_bf16(v1[2], v1[3]);
;                     *(u32x4*)(rowp + bj * HALF) = w; } }
;     __device__ __forceinline__ void done(const pg8::Unit& u) const {
;         const int colt = u.pn * 256;
;         if (even ? !(colt == 512 || colt == 1280 || colt == 1536) : (colt != 1024)) return;
	v_mul_f32_e32 v35, v35, v154
	v_cvt_pk_bf16_f32 v76, v76, v77
	v_cvt_pk_bf16_f32 v77, v84, v85
	global_store_dwordx4 v[78:79], v[74:77], off
	v_mul_f32_e32 v22, v22, v154
	v_mul_f32_e32 v23, v23, v154
	v_mul_f32_e32 v24, v24, v154
	v_mul_f32_e32 v25, v25, v154
	v_mul_f32_e32 v74, v68, v152
	v_mul_f32_e32 v75, v69, v152
	v_mul_f32_e32 v68, v66, v152
	v_mul_f32_e32 v69, v67, v152
	v_cvt_pk_bf16_f32 v66, v70, v71
	v_cvt_pk_bf16_f32 v67, v72, v73
	s_and_b64 vcc, exec, s[72:73]
	v_cvt_pk_bf16_f32 v68, v68, v69
	v_cvt_pk_bf16_f32 v69, v74, v75
	global_store_dwordx4 v[78:79], v[66:69], off offset:256
	v_readlane_b32 s44, v255, 2
	s_nop 0
	v_add_u32_e32 v66, 0x80, v156
	v_mad_i64_i32 v[66:67], s[2:3], v66, s0, 0
	v_lshl_add_u64 v[66:67], v[66:67], 1, s[78:79]
	v_lshl_add_u64 v[66:67], v[66:67], 0, v[158:159]
	v_mul_f32_e32 v68, v60, v144
	v_mul_f32_e32 v69, v61, v144
	v_mul_f32_e32 v60, v58, v144
	v_mul_f32_e32 v61, v59, v144
	v_cvt_pk_bf16_f32 v58, v62, v63
	v_cvt_pk_bf16_f32 v59, v64, v65
	s_nop 0
	v_cvt_pk_bf16_f32 v60, v60, v61
	v_cvt_pk_bf16_f32 v61, v68, v69
	global_store_dwordx4 v[66:67], v[58:61], off
	s_nop 1
	v_mul_f32_e32 v58, v48, v144
	v_mul_f32_e32 v59, v49, v144
	v_mul_f32_e32 v48, v46, v144
	v_mul_f32_e32 v49, v47, v144
	v_cvt_pk_bf16_f32 v46, v54, v55
	v_cvt_pk_bf16_f32 v47, v56, v57
	s_nop 0
	v_cvt_pk_bf16_f32 v48, v48, v49
	v_cvt_pk_bf16_f32 v49, v58, v59
	global_store_dwordx4 v[66:67], v[46:49], off offset:256
	s_nop 1
	v_add_u32_e32 v46, 0x90, v156
	v_mad_i64_i32 v[46:47], s[2:3], v46, s0, 0
	v_lshl_add_u64 v[46:47], v[46:47], 1, s[78:79]
	v_lshl_add_u64 v[46:47], v[46:47], 0, v[158:159]
	v_mul_f32_e32 v48, v52, v145
	v_mul_f32_e32 v49, v53, v145
	v_mul_f32_e32 v52, v44, v145
	v_mul_f32_e32 v53, v45, v145
	v_mul_f32_e32 v44, v42, v145
	v_mul_f32_e32 v45, v43, v145
	v_cvt_pk_bf16_f32 v42, v50, v51
	v_cvt_pk_bf16_f32 v43, v48, v49
	s_nop 0
	v_cvt_pk_bf16_f32 v44, v44, v45
	v_cvt_pk_bf16_f32 v45, v52, v53
	global_store_dwordx4 v[46:47], v[42:45], off
	s_nop 1
	v_mul_f32_e32 v42, v32, v145
	v_mul_f32_e32 v43, v33, v145
	v_mul_f32_e32 v32, v30, v145
	v_mul_f32_e32 v33, v31, v145
	v_cvt_pk_bf16_f32 v30, v38, v39
	v_cvt_pk_bf16_f32 v31, v40, v41
	s_nop 0
	v_cvt_pk_bf16_f32 v32, v32, v33
	v_cvt_pk_bf16_f32 v33, v42, v43
	global_store_dwordx4 v[46:47], v[30:33], off offset:256
	s_nop 1
	v_add_u32_e32 v30, 0xa0, v156
	v_mad_i64_i32 v[30:31], s[2:3], v30, s0, 0
	v_lshl_add_u64 v[30:31], v[30:31], 1, s[78:79]
	v_lshl_add_u64 v[30:31], v[30:31], 0, v[158:159]
	v_mul_f32_e32 v32, v36, v154
	v_mul_f32_e32 v33, v37, v154
	v_mul_f32_e32 v36, v28, v154
	v_mul_f32_e32 v37, v29, v154
	v_mul_f32_e32 v28, v26, v154
	v_mul_f32_e32 v29, v27, v154
	v_cvt_pk_bf16_f32 v26, v34, v35
	v_cvt_pk_bf16_f32 v27, v32, v33
	s_nop 0
	v_cvt_pk_bf16_f32 v28, v28, v29
	v_cvt_pk_bf16_f32 v29, v36, v37
	global_store_dwordx4 v[30:31], v[26:29], off
	s_nop 1
	v_mul_f32_e32 v26, v16, v154
	v_mul_f32_e32 v27, v17, v154
	v_mul_f32_e32 v16, v14, v154
	v_mul_f32_e32 v17, v15, v154
	v_cvt_pk_bf16_f32 v14, v22, v23
	v_cvt_pk_bf16_f32 v15, v24, v25
	s_nop 0
	v_cvt_pk_bf16_f32 v16, v16, v17
	v_cvt_pk_bf16_f32 v17, v26, v27
	global_store_dwordx4 v[30:31], v[14:17], off offset:256
	s_nop 1
	v_add_u32_e32 v14, 0xb0, v156
	v_mad_i64_i32 v[14:15], s[2:3], v14, s0, 0
	v_lshl_add_u64 v[14:15], v[14:15], 1, s[78:79]
	v_mov_b32_e32 v16, v155
	v_lshl_add_u64 v[14:15], v[14:15], 0, v[158:159]
	v_mul_f32_e32 v20, v20, v16
	v_mul_f32_e32 v21, v21, v16
	v_mul_f32_e32 v18, v18, v16
	v_mul_f32_e32 v19, v19, v16
	v_mul_f32_e32 v22, v12, v16
	v_mul_f32_e32 v23, v13, v16
	v_mul_f32_e32 v12, v10, v16
	v_mul_f32_e32 v13, v11, v16
	v_cvt_pk_bf16_f32 v10, v18, v19
	v_cvt_pk_bf16_f32 v11, v20, v21
	v_mul_f32_e32 v8, v8, v16
	v_mul_f32_e32 v9, v9, v16
	v_cvt_pk_bf16_f32 v12, v12, v13
	v_cvt_pk_bf16_f32 v13, v22, v23
	global_store_dwordx4 v[14:15], v[10:13], off
	v_mul_f32_e32 v6, v6, v16
	v_mul_f32_e32 v7, v7, v16
	s_nop 0
	v_mul_f32_e32 v10, v4, v16
	v_mul_f32_e32 v11, v5, v16
	v_mul_f32_e32 v4, v2, v16
	v_mul_f32_e32 v5, v3, v16
	v_cvt_pk_bf16_f32 v2, v6, v7
	v_cvt_pk_bf16_f32 v3, v8, v9
	s_nop 0
	v_cvt_pk_bf16_f32 v4, v4, v5
	v_cvt_pk_bf16_f32 v5, v10, v11
	global_store_dwordx4 v[14:15], v[2:5], off offset:256
	s_cbranch_vccz .LBB0_128
	s_cmp_eq_u32 s6, 4
	s_cselect_b64 s[8:9], -1, 0
	s_cbranch_execz .LBB0_129
	s_branch .LBB0_133

; __device__ __forceinline__ unsigned cvt_pk_bf16(float lo, float hi) { unsigned r; asm volatile("v_cvt_pk_bf16_f32 %0, %1, %2" : "=v"(r) : "v"(lo), "v"(hi)); return r; }
; __device__ __forceinline__ float silu_mul(float g, float u) { const float e = __builtin_amdgcn_exp2f(g * -1.4426950408889634f); return g * __builtin_amdgcn_rcpf(1.0f + e) * u; }
;     __device__ __forceinline__ void operator()(const f32x4 (&acc)[2][2][4][2], const Unit& u, int wr, int wc, int fr, int fq, const float (&rsv)[8]) const {
;         const int row0 = u.pm * BM + wr * 64 + fr; const int col0 = u.pn * HALF + wc * 32 + 8 * fq;
; #pragma unroll
;         for (int ai = 0; ai < 2; ++ai)
; #pragma unroll
;             for (int m = 0; m < 4; ++m) { bf16_t* rowp = O + (size_t)(row0 + ai * HALF + m * 16) * ldc + col0;
;                 const float sc = rsv[4 * ai + m];
;                 const f32x4 g0 = acc[ai][0][m][0] * sc, g1 = acc[ai][0][m][1] * sc, u0 = acc[ai][1][m][0] * sc, u1 = acc[ai][1][m][1] * sc;
;                 u32x4 w; w.x = cvt_pk_bf16(silu_mul(g0[0], u0[0]), silu_mul(g0[1], u0[1])); w.y = cvt_pk_bf16(silu_mul(g0[2], u0[2]), silu_mul(g0[3], u0[3]));
;                 w.z = cvt_pk_bf16(silu_mul(g1[0], u1[0]), silu_mul(g1[1], u1[1])); w.w = cvt_pk_bf16(silu_mul(g1[2], u1[2]), silu_mul(g1[3], u1[3]));
;                 *(u32x4*)rowp = w; }
.LBB0_733:
	s_waitcnt vmcnt(0)
	v_mul_f32_e32 v126, v126, v146
	v_mul_f32_e32 v127, v127, v146
	v_mul_f32_e32 v164, v116, v146
	v_mul_f32_e32 v165, v117, v146
	v_mul_f32_e32 v116, v114, v146
	v_mul_f32_e32 v117, v115, v146
	v_mul_f32_e32 v114, 0xbfb8aa3b, v126
	v_mul_f32_e32 v115, 0xbfb8aa3b, v127
	v_exp_f32_e32 v114, v114
	v_exp_f32_e32 v115, v115
	v_mul_f32_e32 v118, v118, v146
	v_mul_f32_e32 v119, v119, v146
	v_mul_f32_e32 v128, v128, v146
	v_mul_f32_e32 v129, v129, v146
	v_add_f32_e32 v114, 1.0, v114
	v_add_f32_e32 v115, 1.0, v115
	v_rcp_f32_e32 v114, v114
	v_rcp_f32_e32 v115, v115
	v_mul_f32_e32 v120, v120, v146
	v_mul_f32_e32 v121, v121, v146
	v_mul_f32_e32 v122, v122, v146
	v_mul_f32_e32 v123, v123, v146
	v_mul_f32_e32 v114, v126, v114
	v_mul_f32_e32 v115, v127, v115
	v_mul_f32_e32 v114, v118, v114
	v_mul_f32_e32 v115, v119, v115
	v_cvt_pk_bf16_f32 v114, v114, v115
	v_mul_f32_e32 v115, 0xbfb8aa3b, v128
	v_mul_f32_e32 v118, 0xbfb8aa3b, v129
	v_exp_f32_e32 v115, v115
	v_exp_f32_e32 v118, v118
	v_mul_f32_e32 v124, v124, v146
	v_mul_f32_e32 v125, v125, v146
	v_lshl_or_b32 v160, s2, 7, v147
	v_add_f32_e32 v115, 1.0, v115
	v_add_f32_e32 v118, 1.0, v118
	v_rcp_f32_e32 v115, v115
	v_rcp_f32_e32 v118, v118
	v_ashrrev_i32_e32 v161, 31, v160
	v_mov_b64_e32 v[158:159], s[10:11]
	v_mul_f32_e32 v115, v128, v115
	v_mul_f32_e32 v118, v129, v118
	v_mul_f32_e32 v115, v120, v115
	v_mul_f32_e32 v118, v121, v118
	v_cvt_pk_bf16_f32 v115, v115, v118
	v_mul_f32_e32 v118, 0xbfb8aa3b, v122
	v_exp_f32_e32 v118, v118
	s_movk_i32 s15, 0x1600
	v_mad_i64_i32 v[162:163], s[2:3], v156, s15, v[158:159]
	v_add_f32_e32 v118, 1.0, v118
	v_rcp_f32_e32 v118, v118
	v_lshlrev_b64 v[160:161], 1, v[160:161]
	v_lshl_add_u64 v[162:163], v[162:163], 0, v[160:161]
	v_mul_f32_e32 v110, v110, v150
	v_mul_f32_e32 v111, v111, v150
	v_mul_f32_e32 v118, v122, v118
	v_mul_f32_e32 v116, v116, v118
	v_mul_f32_e32 v118, 0xbfb8aa3b, v123
	v_exp_f32_e32 v118, v118
	v_mul_f32_e32 v102, v102, v150
	v_mul_f32_e32 v103, v103, v150
	v_mul_f32_e32 v112, v112, v150
	v_mul_f32_e32 v113, v113, v150
	v_mul_f32_e32 v104, v104, v150
	v_mul_f32_e32 v105, v105, v150
	v_add_f32_e32 v118, 1.0, v118
	v_rcp_f32_e32 v118, v118
	v_mul_f32_e32 v106, v106, v150
	v_mul_f32_e32 v107, v107, v150
	v_mul_f32_e32 v108, v108, v150
	v_mul_f32_e32 v109, v109, v150
	v_mul_f32_e32 v94, v94, v148
	v_mul_f32_e32 v95, v95, v148
	v_mul_f32_e32 v118, v123, v118
	v_mul_f32_e32 v117, v117, v118
	v_cvt_pk_bf16_f32 v116, v116, v117
	v_mul_f32_e32 v117, 0xbfb8aa3b, v124
	v_exp_f32_e32 v117, v117
	v_mul_f32_e32 v118, 0xbfb8aa3b, v125
	v_exp_f32_e32 v118, v118
	v_mul_f32_e32 v86, v86, v148
	v_mul_f32_e32 v87, v87, v148
	v_add_f32_e32 v117, 1.0, v117
	v_rcp_f32_e32 v117, v117
	v_add_f32_e32 v118, 1.0, v118
	v_rcp_f32_e32 v118, v118
	v_mul_f32_e32 v96, v96, v148
	v_mul_f32_e32 v97, v97, v148
	v_mul_f32_e32 v117, v124, v117
	v_mul_f32_e32 v117, v164, v117
	v_mul_f32_e32 v118, v125, v118
	v_mul_f32_e32 v118, v165, v118
	v_cvt_pk_bf16_f32 v117, v117, v118
	global_store_dwordx4 v[162:163], v[114:117], off
	v_mul_f32_e32 v88, v88, v148
	v_mul_f32_e32 v89, v89, v148
	v_mul_f32_e32 v90, v90, v148
	v_mul_f32_e32 v91, v91, v148
	v_mul_f32_e32 v116, v100, v150
	v_mul_f32_e32 v117, v101, v150
	v_mul_f32_e32 v100, v98, v150
	v_mul_f32_e32 v101, v99, v150
	v_mul_f32_e32 v98, 0xbfb8aa3b, v110
	v_mul_f32_e32 v99, 0xbfb8aa3b, v111
	v_exp_f32_e32 v98, v98
	v_exp_f32_e32 v99, v99
	v_or_b32_e32 v114, 16, v156
	v_mad_i64_i32 v[114:115], s[2:3], v114, s15, v[158:159]
	v_add_f32_e32 v98, 1.0, v98
	v_add_f32_e32 v99, 1.0, v99
	v_rcp_f32_e32 v98, v98
	v_rcp_f32_e32 v99, v99
	v_lshl_add_u64 v[114:115], v[114:115], 0, v[160:161]
	v_mul_f32_e32 v92, v92, v148
	v_mul_f32_e32 v93, v93, v148
	v_mul_f32_e32 v98, v110, v98
	v_mul_f32_e32 v99, v111, v99
	v_mul_f32_e32 v98, v102, v98
	v_mul_f32_e32 v99, v103, v99
	v_cvt_pk_bf16_f32 v98, v98, v99
	v_mul_f32_e32 v99, 0xbfb8aa3b, v112
	v_mul_f32_e32 v102, 0xbfb8aa3b, v113
	v_exp_f32_e32 v99, v99
	v_exp_f32_e32 v102, v102
	v_mul_f32_e32 v78, v78, v152
	v_mul_f32_e32 v79, v79, v152
	v_mul_f32_e32 v70, v70, v152
	v_mul_f32_e32 v71, v71, v152
	v_add_f32_e32 v99, 1.0, v99
	v_add_f32_e32 v102, 1.0, v102
	v_rcp_f32_e32 v99, v99
	v_rcp_f32_e32 v102, v102
	v_mul_f32_e32 v80, v80, v152
	v_mul_f32_e32 v81, v81, v152
	v_mul_f32_e32 v72, v72, v152
	v_mul_f32_e32 v73, v73, v152
	v_mul_f32_e32 v99, v112, v99
	v_mul_f32_e32 v102, v113, v102
	v_mul_f32_e32 v99, v104, v99
	v_mul_f32_e32 v102, v105, v102
	v_cvt_pk_bf16_f32 v99, v99, v102
	v_mul_f32_e32 v102, 0xbfb8aa3b, v106
	v_exp_f32_e32 v102, v102
	v_mul_f32_e32 v74, v74, v152
	v_mul_f32_e32 v75, v75, v152
	v_mul_f32_e32 v76, v76, v152
	v_mul_f32_e32 v77, v77, v152
	v_mul_f32_e32 v62, v62, v144
	v_mul_f32_e32 v63, v63, v144
	v_add_f32_e32 v102, 1.0, v102
	v_rcp_f32_e32 v102, v102
	v_mul_f32_e32 v54, v54, v144
	v_mul_f32_e32 v55, v55, v144
	v_mul_f32_e32 v64, v64, v144
	v_mul_f32_e32 v65, v65, v144
	v_mul_f32_e32 v56, v56, v144
	v_mul_f32_e32 v57, v57, v144
	v_mul_f32_e32 v102, v106, v102
	v_mul_f32_e32 v100, v100, v102
	v_mul_f32_e32 v102, 0xbfb8aa3b, v107
	v_exp_f32_e32 v102, v102
	v_mul_f32_e32 v58, v58, v144
	v_mul_f32_e32 v59, v59, v144
	v_mul_f32_e32 v60, v60, v144
	v_mul_f32_e32 v61, v61, v144
	v_mul_f32_e32 v46, v46, v145
	v_mul_f32_e32 v47, v47, v145
	v_add_f32_e32 v102, 1.0, v102
	v_rcp_f32_e32 v102, v102
	v_mul_f32_e32 v38, v38, v145
	v_mul_f32_e32 v39, v39, v145
	v_mul_f32_e32 v48, v48, v145
	v_mul_f32_e32 v49, v49, v145
	v_mul_f32_e32 v40, v40, v145
	v_mul_f32_e32 v41, v41, v145
	v_mul_f32_e32 v102, v107, v102
	v_mul_f32_e32 v101, v101, v102
	v_cvt_pk_bf16_f32 v100, v100, v101
; __device__ __forceinline__ unsigned cvt_pk_bf16(float lo, float hi) { unsigned r; asm volatile("v_cvt_pk_bf16_f32 %0, %1, %2" : "=v"(r) : "v"(lo), "v"(hi)); return r; }
; __device__ __forceinline__ float silu_mul(float g, float u) { const float e = __builtin_amdgcn_exp2f(g * -1.4426950408889634f); return g * __builtin_amdgcn_rcpf(1.0f + e) * u; }
;     __device__ __forceinline__ void operator()(const f32x4 (&acc)[2][2][4][2], const Unit& u, int wr, int wc, int fr, int fq, const float (&rsv)[8]) const {
;         const int row0 = u.pm * BM + wr * 64 + fr; const int col0 = u.pn * HALF + wc * 32 + 8 * fq;
; #pragma unroll
;         for (int ai = 0; ai < 2; ++ai)
; #pragma unroll
;             for (int m = 0; m < 4; ++m) { bf16_t* rowp = O + (size_t)(row0 + ai * HALF + m * 16) * ldc + col0;
;                 const float sc = rsv[4 * ai + m];
;                 const f32x4 g0 = acc[ai][0][m][0] * sc, g1 = acc[ai][0][m][1] * sc, u0 = acc[ai][1][m][0] * sc, u1 = acc[ai][1][m][1] * sc;
;                 u32x4 w; w.x = cvt_pk_bf16(silu_mul(g0[0], u0[0]), silu_mul(g0[1], u0[1])); w.y = cvt_pk_bf16(silu_mul(g0[2], u0[2]), silu_mul(g0[3], u0[3]));
;                 w.z = cvt_pk_bf16(silu_mul(g1[0], u1[0]), silu_mul(g1[1], u1[1])); w.w = cvt_pk_bf16(silu_mul(g1[2], u1[2]), silu_mul(g1[3], u1[3]));
;                 *(u32x4*)rowp = w; }
	v_mul_f32_e32 v101, 0xbfb8aa3b, v108
	v_exp_f32_e32 v101, v101
	v_mul_f32_e32 v102, 0xbfb8aa3b, v109
	v_exp_f32_e32 v102, v102
	v_mul_f32_e32 v42, v42, v145
	v_mul_f32_e32 v43, v43, v145
	v_add_f32_e32 v101, 1.0, v101
	v_rcp_f32_e32 v101, v101
	v_add_f32_e32 v102, 1.0, v102
	v_rcp_f32_e32 v102, v102
	v_mul_f32_e32 v44, v44, v145
	v_mul_f32_e32 v45, v45, v145
	v_mul_f32_e32 v101, v108, v101
	v_mul_f32_e32 v101, v116, v101
	v_mul_f32_e32 v102, v109, v102
	v_mul_f32_e32 v102, v117, v102
	v_cvt_pk_bf16_f32 v101, v101, v102
	global_store_dwordx4 v[114:115], v[98:101], off
	v_mul_f32_e32 v30, v30, v154
	v_mul_f32_e32 v31, v31, v154
	v_mul_f32_e32 v22, v22, v154
	v_mul_f32_e32 v23, v23, v154
	v_mul_f32_e32 v100, v84, v148
	v_mul_f32_e32 v101, v85, v148
	v_mul_f32_e32 v84, v82, v148
	v_mul_f32_e32 v85, v83, v148
	v_mul_f32_e32 v82, 0xbfb8aa3b, v94
	v_mul_f32_e32 v83, 0xbfb8aa3b, v95
	v_exp_f32_e32 v82, v82
	v_exp_f32_e32 v83, v83
	v_or_b32_e32 v98, 32, v156
	v_mad_i64_i32 v[98:99], s[2:3], v98, s15, v[158:159]
	v_add_f32_e32 v82, 1.0, v82
	v_add_f32_e32 v83, 1.0, v83
	v_rcp_f32_e32 v82, v82
	v_rcp_f32_e32 v83, v83
	v_lshl_add_u64 v[98:99], v[98:99], 0, v[160:161]
	v_mul_f32_e32 v32, v32, v154
	v_mul_f32_e32 v33, v33, v154
	v_mul_f32_e32 v82, v94, v82
	v_mul_f32_e32 v83, v95, v83
	v_mul_f32_e32 v82, v86, v82
	v_mul_f32_e32 v83, v87, v83
	v_cvt_pk_bf16_f32 v82, v82, v83
	v_mul_f32_e32 v83, 0xbfb8aa3b, v96
	v_mul_f32_e32 v86, 0xbfb8aa3b, v97
	v_exp_f32_e32 v83, v83
	v_exp_f32_e32 v86, v86
	v_mul_f32_e32 v24, v24, v154
	v_mul_f32_e32 v25, v25, v154
	v_mul_f32_e32 v26, v26, v154
	v_mul_f32_e32 v27, v27, v154
	v_add_f32_e32 v83, 1.0, v83
	v_add_f32_e32 v86, 1.0, v86
	v_rcp_f32_e32 v83, v83
	v_rcp_f32_e32 v86, v86
	v_mul_f32_e32 v28, v28, v154
	v_mul_f32_e32 v29, v29, v154
	v_mul_f32_e32 v14, v14, v142
	v_mul_f32_e32 v15, v15, v142
	v_mul_f32_e32 v83, v96, v83
	v_mul_f32_e32 v86, v97, v86
	v_mul_f32_e32 v83, v88, v83
	v_mul_f32_e32 v86, v89, v86
	v_cvt_pk_bf16_f32 v83, v83, v86
	v_mul_f32_e32 v86, 0xbfb8aa3b, v90
	v_exp_f32_e32 v86, v86
	v_mul_f32_e32 v6, v6, v142
	v_mul_f32_e32 v7, v7, v142
	v_mul_f32_e32 v16, v16, v142
	v_mul_f32_e32 v17, v17, v142
	v_mul_f32_e32 v8, v8, v142
	v_mul_f32_e32 v9, v9, v142
	v_add_f32_e32 v86, 1.0, v86
	v_rcp_f32_e32 v86, v86
	v_mul_f32_e32 v10, v10, v142
	v_mul_f32_e32 v11, v11, v142
	v_mul_f32_e32 v12, v12, v142
	v_mul_f32_e32 v13, v13, v142
	s_mov_b64 s[20:21], -1
	v_mul_f32_e32 v86, v90, v86
	v_mul_f32_e32 v84, v84, v86
	v_mul_f32_e32 v86, 0xbfb8aa3b, v91
	v_exp_f32_e32 v86, v86
	s_andn2_b64 vcc, exec, s[6:7]
	v_add_f32_e32 v86, 1.0, v86
	v_rcp_f32_e32 v86, v86
	s_nop 0
	v_mul_f32_e32 v86, v91, v86
	v_mul_f32_e32 v85, v85, v86
	v_cvt_pk_bf16_f32 v84, v84, v85
	v_mul_f32_e32 v85, 0xbfb8aa3b, v92
	v_exp_f32_e32 v85, v85
	v_mul_f32_e32 v86, 0xbfb8aa3b, v93
	v_exp_f32_e32 v86, v86
	v_add_f32_e32 v85, 1.0, v85
	v_rcp_f32_e32 v85, v85
	v_add_f32_e32 v86, 1.0, v86
	v_rcp_f32_e32 v86, v86
	v_mul_f32_e32 v85, v92, v85
	v_mul_f32_e32 v85, v100, v85
	v_mul_f32_e32 v86, v93, v86
	v_mul_f32_e32 v86, v101, v86
	v_cvt_pk_bf16_f32 v85, v85, v86
	global_store_dwordx4 v[98:99], v[82:85], off
	s_nop 1
	v_mul_f32_e32 v84, v68, v152
	v_mul_f32_e32 v85, v69, v152
	v_mul_f32_e32 v68, v66, v152
	v_mul_f32_e32 v69, v67, v152
	v_mul_f32_e32 v66, 0xbfb8aa3b, v78
	v_mul_f32_e32 v67, 0xbfb8aa3b, v79
	v_exp_f32_e32 v66, v66
	v_exp_f32_e32 v67, v67
	v_or_b32_e32 v82, 48, v156
	v_mad_i64_i32 v[82:83], s[2:3], v82, s15, v[158:159]
	v_add_f32_e32 v66, 1.0, v66
	v_add_f32_e32 v67, 1.0, v67
	v_rcp_f32_e32 v66, v66
	v_rcp_f32_e32 v67, v67
	v_lshl_add_u64 v[82:83], v[82:83], 0, v[160:161]
	v_mul_f32_e32 v66, v78, v66
	v_mul_f32_e32 v67, v79, v67
	v_mul_f32_e32 v66, v70, v66
	v_mul_f32_e32 v67, v71, v67
	v_cvt_pk_bf16_f32 v66, v66, v67
	v_mul_f32_e32 v67, 0xbfb8aa3b, v80
	v_mul_f32_e32 v70, 0xbfb8aa3b, v81
	v_exp_f32_e32 v67, v67
	v_exp_f32_e32 v70, v70
	v_add_f32_e32 v67, 1.0, v67
	v_add_f32_e32 v70, 1.0, v70
	v_rcp_f32_e32 v67, v67
	v_rcp_f32_e32 v70, v70
	v_mul_f32_e32 v67, v80, v67
	v_mul_f32_e32 v70, v81, v70
	v_mul_f32_e32 v67, v72, v67
	v_mul_f32_e32 v70, v73, v70
	v_cvt_pk_bf16_f32 v67, v67, v70
	v_mul_f32_e32 v70, 0xbfb8aa3b, v74
	v_exp_f32_e32 v70, v70
	s_nop 0
	v_add_f32_e32 v70, 1.0, v70
	v_rcp_f32_e32 v70, v70
	s_nop 0
	v_mul_f32_e32 v70, v74, v70
	v_mul_f32_e32 v68, v68, v70
	v_mul_f32_e32 v70, 0xbfb8aa3b, v75
	v_exp_f32_e32 v70, v70
	s_nop 0
	v_add_f32_e32 v70, 1.0, v70
	v_rcp_f32_e32 v70, v70
	s_nop 0
	v_mul_f32_e32 v70, v75, v70
	v_mul_f32_e32 v69, v69, v70
	v_cvt_pk_bf16_f32 v68, v68, v69
	v_mul_f32_e32 v69, 0xbfb8aa3b, v76
	v_exp_f32_e32 v69, v69
	v_mul_f32_e32 v70, 0xbfb8aa3b, v77
	v_exp_f32_e32 v70, v70
	v_add_f32_e32 v69, 1.0, v69
	v_rcp_f32_e32 v69, v69
	v_add_f32_e32 v70, 1.0, v70
	v_rcp_f32_e32 v70, v70
	v_mul_f32_e32 v69, v76, v69
	v_mul_f32_e32 v69, v84, v69
	v_mul_f32_e32 v70, v77, v70
	v_mul_f32_e32 v70, v85, v70
	v_cvt_pk_bf16_f32 v69, v69, v70
	global_store_dwordx4 v[82:83], v[66:69], off
	s_nop 1
	v_mul_f32_e32 v68, v52, v144
	v_mul_f32_e32 v69, v53, v144
	v_mul_f32_e32 v52, v50, v144
	v_mul_f32_e32 v53, v51, v144
	v_mul_f32_e32 v50, 0xbfb8aa3b, v62
	v_mul_f32_e32 v51, 0xbfb8aa3b, v63
	v_exp_f32_e32 v50, v50
	v_exp_f32_e32 v51, v51
	v_add_u32_e32 v66, 0x80, v156
	v_mad_i64_i32 v[66:67], s[2:3], v66, s15, v[158:159]
	v_add_f32_e32 v50, 1.0, v50
	v_add_f32_e32 v51, 1.0, v51
	v_rcp_f32_e32 v50, v50
	v_rcp_f32_e32 v51, v51
	v_lshl_add_u64 v[66:67], v[66:67], 0, v[160:161]
	v_mul_f32_e32 v50, v62, v50
	v_mul_f32_e32 v51, v63, v51
	v_mul_f32_e32 v50, v54, v50
	v_mul_f32_e32 v51, v55, v51
	v_cvt_pk_bf16_f32 v50, v50, v51
; __device__ __forceinline__ unsigned cvt_pk_bf16(float lo, float hi) { unsigned r; asm volatile("v_cvt_pk_bf16_f32 %0, %1, %2" : "=v"(r) : "v"(lo), "v"(hi)); return r; }
; __device__ __forceinline__ float silu_mul(float g, float u) { const float e = __builtin_amdgcn_exp2f(g * -1.4426950408889634f); return g * __builtin_amdgcn_rcpf(1.0f + e) * u; }
;     __device__ __forceinline__ void operator()(const f32x4 (&acc)[2][2][4][2], const Unit& u, int wr, int wc, int fr, int fq, const float (&rsv)[8]) const {
;         const int row0 = u.pm * BM + wr * 64 + fr; const int col0 = u.pn * HALF + wc * 32 + 8 * fq;
; #pragma unroll
;         for (int ai = 0; ai < 2; ++ai)
; #pragma unroll
;             for (int m = 0; m < 4; ++m) { bf16_t* rowp = O + (size_t)(row0 + ai * HALF + m * 16) * ldc + col0;
;                 const float sc = rsv[4 * ai + m];
;                 const f32x4 g0 = acc[ai][0][m][0] * sc, g1 = acc[ai][0][m][1] * sc, u0 = acc[ai][1][m][0] * sc, u1 = acc[ai][1][m][1] * sc;
;                 u32x4 w; w.x = cvt_pk_bf16(silu_mul(g0[0], u0[0]), silu_mul(g0[1], u0[1])); w.y = cvt_pk_bf16(silu_mul(g0[2], u0[2]), silu_mul(g0[3], u0[3]));
;                 w.z = cvt_pk_bf16(silu_mul(g1[0], u1[0]), silu_mul(g1[1], u1[1])); w.w = cvt_pk_bf16(silu_mul(g1[2], u1[2]), silu_mul(g1[3], u1[3]));
;                 *(u32x4*)rowp = w; }
	v_mul_f32_e32 v51, 0xbfb8aa3b, v64
	v_mul_f32_e32 v54, 0xbfb8aa3b, v65
	v_exp_f32_e32 v51, v51
	v_exp_f32_e32 v54, v54
	v_add_f32_e32 v51, 1.0, v51
	v_add_f32_e32 v54, 1.0, v54
	v_rcp_f32_e32 v51, v51
	v_rcp_f32_e32 v54, v54
	v_mul_f32_e32 v51, v64, v51
	v_mul_f32_e32 v54, v65, v54
	v_mul_f32_e32 v51, v56, v51
	v_mul_f32_e32 v54, v57, v54
	v_cvt_pk_bf16_f32 v51, v51, v54
	v_mul_f32_e32 v54, 0xbfb8aa3b, v58
	v_exp_f32_e32 v54, v54
	s_nop 0
	v_add_f32_e32 v54, 1.0, v54
	v_rcp_f32_e32 v54, v54
	s_nop 0
	v_mul_f32_e32 v54, v58, v54
	v_mul_f32_e32 v52, v52, v54
	v_mul_f32_e32 v54, 0xbfb8aa3b, v59
	v_exp_f32_e32 v54, v54
	s_nop 0
	v_add_f32_e32 v54, 1.0, v54
	v_rcp_f32_e32 v54, v54
	s_nop 0
	v_mul_f32_e32 v54, v59, v54
	v_mul_f32_e32 v53, v53, v54
	v_cvt_pk_bf16_f32 v52, v52, v53
	v_mul_f32_e32 v53, 0xbfb8aa3b, v60
	v_exp_f32_e32 v53, v53
	v_mul_f32_e32 v54, 0xbfb8aa3b, v61
	v_exp_f32_e32 v54, v54
	v_add_f32_e32 v53, 1.0, v53
	v_rcp_f32_e32 v53, v53
	v_add_f32_e32 v54, 1.0, v54
	v_rcp_f32_e32 v54, v54
	v_mul_f32_e32 v53, v60, v53
	v_mul_f32_e32 v53, v68, v53
	v_mul_f32_e32 v54, v61, v54
	v_mul_f32_e32 v54, v69, v54
	v_cvt_pk_bf16_f32 v53, v53, v54
	global_store_dwordx4 v[66:67], v[50:53], off
	s_nop 1
	v_mul_f32_e32 v52, v36, v145
	v_mul_f32_e32 v53, v37, v145
	v_mul_f32_e32 v36, v34, v145
	v_mul_f32_e32 v37, v35, v145
	v_mul_f32_e32 v34, 0xbfb8aa3b, v46
	v_mul_f32_e32 v35, 0xbfb8aa3b, v47
	v_exp_f32_e32 v34, v34
	v_exp_f32_e32 v35, v35
	v_add_u32_e32 v50, 0x90, v156
	v_mad_i64_i32 v[50:51], s[2:3], v50, s15, v[158:159]
	v_add_f32_e32 v34, 1.0, v34
	v_add_f32_e32 v35, 1.0, v35
	v_rcp_f32_e32 v34, v34
	v_rcp_f32_e32 v35, v35
	v_lshl_add_u64 v[50:51], v[50:51], 0, v[160:161]
	v_mul_f32_e32 v34, v46, v34
	v_mul_f32_e32 v35, v47, v35
	v_mul_f32_e32 v34, v38, v34
	v_mul_f32_e32 v35, v39, v35
	v_cvt_pk_bf16_f32 v34, v34, v35
	v_mul_f32_e32 v35, 0xbfb8aa3b, v48
	v_mul_f32_e32 v38, 0xbfb8aa3b, v49
	v_exp_f32_e32 v35, v35
	v_exp_f32_e32 v38, v38
	v_add_f32_e32 v35, 1.0, v35
	v_add_f32_e32 v38, 1.0, v38
	v_rcp_f32_e32 v35, v35
	v_rcp_f32_e32 v38, v38
	v_mul_f32_e32 v35, v48, v35
	v_mul_f32_e32 v38, v49, v38
	v_mul_f32_e32 v35, v40, v35
	v_mul_f32_e32 v38, v41, v38
	v_cvt_pk_bf16_f32 v35, v35, v38
	v_mul_f32_e32 v38, 0xbfb8aa3b, v42
	v_exp_f32_e32 v38, v38
	s_nop 0
	v_add_f32_e32 v38, 1.0, v38
	v_rcp_f32_e32 v38, v38
	s_nop 0
	v_mul_f32_e32 v38, v42, v38
	v_mul_f32_e32 v36, v36, v38
	v_mul_f32_e32 v38, 0xbfb8aa3b, v43
	v_exp_f32_e32 v38, v38
	s_nop 0
	v_add_f32_e32 v38, 1.0, v38
	v_rcp_f32_e32 v38, v38
	s_nop 0
	v_mul_f32_e32 v38, v43, v38
	v_mul_f32_e32 v37, v37, v38
	v_cvt_pk_bf16_f32 v36, v36, v37
	v_mul_f32_e32 v37, 0xbfb8aa3b, v44
	v_exp_f32_e32 v37, v37
	v_mul_f32_e32 v38, 0xbfb8aa3b, v45
	v_exp_f32_e32 v38, v38
	v_add_f32_e32 v37, 1.0, v37
	v_rcp_f32_e32 v37, v37
	v_add_f32_e32 v38, 1.0, v38
	v_rcp_f32_e32 v38, v38
	v_mul_f32_e32 v37, v44, v37
	v_mul_f32_e32 v37, v52, v37
	v_mul_f32_e32 v38, v45, v38
	v_mul_f32_e32 v38, v53, v38
	v_cvt_pk_bf16_f32 v37, v37, v38
	global_store_dwordx4 v[50:51], v[34:37], off
	s_nop 1
	v_mul_f32_e32 v36, v20, v154
	v_mul_f32_e32 v37, v21, v154
	v_mul_f32_e32 v20, v18, v154
	v_mul_f32_e32 v21, v19, v154
	v_mul_f32_e32 v18, 0xbfb8aa3b, v30
	v_mul_f32_e32 v19, 0xbfb8aa3b, v31
	v_exp_f32_e32 v18, v18
	v_exp_f32_e32 v19, v19
	v_add_u32_e32 v34, 0xa0, v156
	v_mad_i64_i32 v[34:35], s[2:3], v34, s15, v[158:159]
	v_add_f32_e32 v18, 1.0, v18
	v_add_f32_e32 v19, 1.0, v19
	v_rcp_f32_e32 v18, v18
	v_rcp_f32_e32 v19, v19
	v_lshl_add_u64 v[34:35], v[34:35], 0, v[160:161]
	v_mul_f32_e32 v18, v30, v18
	v_mul_f32_e32 v19, v31, v19
	v_mul_f32_e32 v18, v22, v18
	v_mul_f32_e32 v19, v23, v19
	v_cvt_pk_bf16_f32 v18, v18, v19
	v_mul_f32_e32 v19, 0xbfb8aa3b, v32
	v_mul_f32_e32 v22, 0xbfb8aa3b, v33
	v_exp_f32_e32 v19, v19
	v_exp_f32_e32 v22, v22
	v_add_f32_e32 v19, 1.0, v19
	v_add_f32_e32 v22, 1.0, v22
	v_rcp_f32_e32 v19, v19
	v_rcp_f32_e32 v22, v22
	v_mul_f32_e32 v19, v32, v19
	v_mul_f32_e32 v22, v33, v22
	v_mul_f32_e32 v19, v24, v19
	v_mul_f32_e32 v22, v25, v22
	v_cvt_pk_bf16_f32 v19, v19, v22
	v_mul_f32_e32 v22, 0xbfb8aa3b, v26
	v_exp_f32_e32 v22, v22
	s_nop 0
	v_add_f32_e32 v22, 1.0, v22
	v_rcp_f32_e32 v22, v22
	s_nop 0
	v_mul_f32_e32 v22, v26, v22
	v_mul_f32_e32 v20, v20, v22
	v_mul_f32_e32 v22, 0xbfb8aa3b, v27
	v_exp_f32_e32 v22, v22
	s_nop 0
	v_add_f32_e32 v22, 1.0, v22
	v_rcp_f32_e32 v22, v22
	s_nop 0
	v_mul_f32_e32 v22, v27, v22
	v_mul_f32_e32 v21, v21, v22
	v_cvt_pk_bf16_f32 v20, v20, v21
	v_mul_f32_e32 v21, 0xbfb8aa3b, v28
	v_exp_f32_e32 v21, v21
	v_mul_f32_e32 v22, 0xbfb8aa3b, v29
	v_exp_f32_e32 v22, v22
	v_add_f32_e32 v21, 1.0, v21
	v_rcp_f32_e32 v21, v21
	v_add_f32_e32 v22, 1.0, v22
	v_rcp_f32_e32 v22, v22
	v_mul_f32_e32 v21, v28, v21
	v_mul_f32_e32 v21, v36, v21
	v_mul_f32_e32 v22, v29, v22
	v_mul_f32_e32 v22, v37, v22
	v_cvt_pk_bf16_f32 v21, v21, v22
	global_store_dwordx4 v[34:35], v[18:21], off
	s_nop 1
	v_mul_f32_e32 v20, v4, v142
	v_mul_f32_e32 v21, v5, v142
	v_mul_f32_e32 v4, v2, v142
	v_mul_f32_e32 v5, v3, v142
	v_mul_f32_e32 v2, 0xbfb8aa3b, v14
	v_mul_f32_e32 v3, 0xbfb8aa3b, v15
	v_exp_f32_e32 v2, v2
	v_exp_f32_e32 v3, v3
	v_add_u32_e32 v18, 0xb0, v156
	v_mad_i64_i32 v[18:19], s[2:3], v18, s15, v[158:159]
	v_add_f32_e32 v2, 1.0, v2
	v_add_f32_e32 v3, 1.0, v3
	v_rcp_f32_e32 v2, v2
	v_rcp_f32_e32 v3, v3
	v_lshl_add_u64 v[18:19], v[18:19], 0, v[160:161]
	v_mul_f32_e32 v2, v14, v2
	v_mul_f32_e32 v3, v15, v3
	v_mul_f32_e32 v2, v6, v2
	v_mul_f32_e32 v3, v7, v3
	v_cvt_pk_bf16_f32 v2, v2, v3
	v_mul_f32_e32 v3, 0xbfb8aa3b, v16
	v_mul_f32_e32 v6, 0xbfb8aa3b, v17
	v_exp_f32_e32 v3, v3
	v_exp_f32_e32 v6, v6
	v_add_f32_e32 v3, 1.0, v3
	v_add_f32_e32 v6, 1.0, v6
	v_rcp_f32_e32 v3, v3
	v_rcp_f32_e32 v6, v6
	v_mul_f32_e32 v3, v16, v3
	v_mul_f32_e32 v6, v17, v6
	v_mul_f32_e32 v3, v8, v3
	v_mul_f32_e32 v6, v9, v6
	v_cvt_pk_bf16_f32 v3, v3, v6
	v_mul_f32_e32 v6, 0xbfb8aa3b, v10
	v_exp_f32_e32 v6, v6
	s_nop 0
	v_add_f32_e32 v6, 1.0, v6
	v_rcp_f32_e32 v6, v6
	s_nop 0
	v_mul_f32_e32 v6, v10, v6
	v_mul_f32_e32 v4, v4, v6
	v_mul_f32_e32 v6, 0xbfb8aa3b, v11
	v_exp_f32_e32 v6, v6
	s_nop 0
	v_add_f32_e32 v6, 1.0, v6
	v_rcp_f32_e32 v6, v6
	s_nop 0
	v_mul_f32_e32 v6, v11, v6
	v_mul_f32_e32 v5, v5, v6
	v_cvt_pk_bf16_f32 v4, v4, v5
	v_mul_f32_e32 v5, 0xbfb8aa3b, v12
	v_exp_f32_e32 v5, v5
	v_mul_f32_e32 v6, 0xbfb8aa3b, v13
	v_exp_f32_e32 v6, v6
	v_add_f32_e32 v5, 1.0, v5
	v_rcp_f32_e32 v5, v5
	v_add_f32_e32 v6, 1.0, v6
	v_rcp_f32_e32 v6, v6
	v_mul_f32_e32 v5, v12, v5
	v_mul_f32_e32 v5, v20, v5
	v_mul_f32_e32 v6, v13, v6
	v_mul_f32_e32 v6, v21, v6
	v_cvt_pk_bf16_f32 v5, v5, v6
	global_store_dwordx4 v[18:19], v[2:5], off
	s_cbranch_vccnz .LBB0_724
	s_andn2_b64 vcc, exec, s[8:9]
	s_cbranch_vccnz .LBB0_723
	s_barrier
	s_branch .LBB0_723
